# even_prep: static s_setprio 1 for waves 0-3 (the solve waves) on top of attention younger-half raise
# speedup vs baseline: 1.0014x; 1.0014x over previous
; #define LAS __attribute__((address_space(3)))
; __device__ __forceinline__ void even_prep(const Ctx& c, const Params& p, int e) {
;     ...
;     const bf16_t* HALO = (const bf16_t*)(c.ws + WS_HALO); const float* GCB = (const float*)(c.ws + WS_GCB);
;     bf16_t* Zw = (bf16_t*)(c.ws + WS_Z);
;     LAS bf16_t* KN = (LAS bf16_t*)(c.lds);
;     LAS float* VB = (LAS float*)(c.lds + 17408);
;     LAS float* KBG = (LAS float*)(c.lds + 17408 + 32768);
;     LAS float* Lm = (LAS float*)(c.lds + 17408 + 65536);
;     LAS float* sgc = (LAS float*)(c.lds + 17408 + 65536 + 16384);
;     LAS float* sbeta = sgc + 64;
;     LAS bf16_t* QS = (LAS bf16_t*)(c.lds + 17408 + 65536 + 16384 + 512);
;     for (int item = c.bid; item < 3072; item += c.G) {
;         int tid_i = c.tid; asm volatile("" : "+v"(tid_i)); const int lane_i = tid_i & 63;
;         const int n = item & 127, bh = item >> 7, h = bh % 6, b = bh / 6; const int m0 = b * T_ + 64 * n;
;         if (tid_i < 128) sgc[tid_i] = GCB[(size_t)item * 128 + tid_i];
;         __syncthreads();
;         const float glast = sgc[63];
;         u32x4 qdp0 = {}, qdp1 = {}, kdp0 = {}, kdp1 = {};
.LBB0_544:
	s_or_b64 exec, exec, s[2:3]
	s_cmpk_gt_i32 s94, 0xbff
	s_movk_i32 s1, 0x2000
	s_cbranch_scc1 .LBB0_793
	s_cmp_lt_i32 s46, 4
	s_cbranch_scc0 .Levp_noprio
	s_setprio 1
.Levp_noprio:
	s_add_u32 s18, s22, 0x1d400000
	s_addc_u32 s19, s23, 0
	s_add_u32 s36, s22, 0x1dc00000
	s_addc_u32 s0, s23, 0
	v_writelane_b32 v255, s0, 45
	s_add_i32 s39, s80, 0x4400
	v_readlane_b32 s2, v255, 39
	s_add_i32 s42, s80, 0xc400
	s_add_i32 s48, s80, 0x14400
	s_add_i32 s49, s80, 0x18400
	s_add_i32 s58, s80, 0x18500
	s_add_i32 s59, s80, 0x18600
	s_mul_i32 s2, s2, 0x9000
	s_add_u32 s72, s6, s2
	s_addc_u32 s73, s7, 0
	s_add_i32 s95, s80, 0x184fc
	s_add_u32 s96, s72, 0x1800
	s_addc_u32 s97, s73, 0
	s_and_b32 s2, s46, 3
	s_cmp_lg_u32 s2, 3
	s_cselect_b64 s[20:21], -1, 0
	s_cmp_lt_i32 s46, 4
	v_readlane_b32 s3, v255, 40
	s_cselect_b64 s[24:25], -1, 0
	s_cmp_gt_i32 s46, 3
	s_cselect_b32 s3, s59, s80
	s_cmp_eq_u32 s2, 0
	s_cselect_b32 s31, 0, 32
	s_lshl_b32 s2, s46, 4
	v_writelane_b32 v255, s3, 49
	s_and_b32 s0, s2, 32
	v_writelane_b32 v255, s0, 51
	s_mov_b32 s26, s94

; __device__ __forceinline__ void even_prep(const Ctx& c, const Params& p, int e) {
;     ...
;         __syncthreads();
;     }
; }
.LBB0_793:
	s_setprio 0
	v_readlane_b32 s44, v255, 47
	s_mov_b64 s[2:3], 0
	s_mov_b64 s[4:5], 0
	v_readlane_b32 s45, v255, 48
